# v094 + branch-GEMM epilogue hbuf stores lane-transposed via ds_bpermute (4 neighbouring lanes write one row's 64 B), each store issued one site later
# baseline (speedup 1.0000x reference)
; __device__ __forceinline__ unsigned cvtpk(float lo, float hi) { unsigned r; asm volatile("v_cvt_pk_bf16_f32 %0, %1, %2" : "=v"(r) : "v"(lo), "v"(hi)); return r; }
;     __device__ __forceinline__ void operator()(f32x4 (&acc)[2][2][4][2], const pg8::Unit& u, int wr, int wc, int fr, int fq) const {
;         const int row0 = u.pm * 256 + wr * 64 + fr, cin = wc * 32 + 8 * fq; const bool last = (u.pn >= 12);
; #pragma unroll
;         for (int ai = 0; ai < 2; ++ai) {
;             u32x2 ga[4][2], gb[4][2];
; #pragma unroll
;             for (int m = 0; m < 4; ++m) {
;                 const unsigned char* gp = gq + (size_t)(row0 + ai * 128 + m * 16) * 4096 + u.pn * 256 + cin;
; #pragma unroll
;                 for (int bj = 0; bj < 2; ++bj) { ga[m][bj] = *(const u32x2*)(gp + bj * 128);
;                     gb[m][bj] = last ? (u32x2){0x01010101u, 0x01010101u} : *(const u32x2*)(gp + 1024 + bj * 128); }
;             }
; #pragma unroll
;             for (int m = 0; m < 4; ++m) {
;                 u16* op = hbuf + (size_t)(row0 + ai * 128 + m * 16) * DM + (u.pn & 3) * 256 + cin;
; #pragma unroll
;                 for (int bj = 0; bj < 2; ++bj) {
;                     f32x4 vv[2];
; #pragma unroll
;                     for (int n = 0; n < 2; ++n) {
;                         const unsigned a4 = ga[m][bj][n], b4 = gb[m][bj][n]; f32x4 v = acc[ai][bj][m][n];
; #pragma unroll
;                         for (int j = 0; j < 4; ++j) { const float ga_ = fmaxf((float)((a4 >> (8 * j)) & 255u), 1.f), gb_ = fmaxf((float)((b4 >> (8 * j)) & 255u), 1.f);
;                             v[j] *= last ? ga_ * (1.f / 255.f) : ga_ * __builtin_amdgcn_rcpf(gb_); }
;                         vv[n] = v; if (!last) acc[ai][bj][m][n] = v;
;                     }
;                     if (last) { u32x4 o = {cvtpk(vv[0][0], vv[0][1]), cvtpk(vv[0][2], vv[0][3]), cvtpk(vv[1][0], vv[1][1]), cvtpk(vv[1][2], vv[1][3])}; *(u32x4*)(op + bj * 128) = o; }
.LBB0_40:
	v_lshlrev_b64 v[194:195], 11, v[144:145]
	s_waitcnt vmcnt(0)
	v_and_b32_e32 v213, 15, v198
	v_bfe_u32 v214, v198, 4, 2
	v_lshl_or_b32 v213, v213, 2, v214
	v_lshlrev_b32_e32 v213, 2, v213
	ds_bpermute_b32 v192, v213, v192
	ds_bpermute_b32 v193, v213, v193
	ds_bpermute_b32 v196, v213, v196
	ds_bpermute_b32 v197, v213, v197
	ds_bpermute_b32 v190, v213, v190
	ds_bpermute_b32 v191, v213, v191
	ds_bpermute_b32 v188, v213, v188
	ds_bpermute_b32 v189, v213, v189
	ds_bpermute_b32 v182, v213, v182
	ds_bpermute_b32 v183, v213, v183
	ds_bpermute_b32 v184, v213, v184
	ds_bpermute_b32 v185, v213, v185
	ds_bpermute_b32 v180, v213, v180
	ds_bpermute_b32 v181, v213, v181
	ds_bpermute_b32 v178, v213, v178
	s_waitcnt lgkmcnt(7)
	ds_bpermute_b32 v179, v213, v179
	ds_bpermute_b32 v172, v213, v172
	ds_bpermute_b32 v173, v213, v173
	ds_bpermute_b32 v174, v213, v174
	ds_bpermute_b32 v175, v213, v175
	ds_bpermute_b32 v160, v213, v160
	ds_bpermute_b32 v161, v213, v161
	ds_bpermute_b32 v158, v213, v158
	s_waitcnt lgkmcnt(7)
	ds_bpermute_b32 v159, v213, v159
	ds_bpermute_b32 v152, v213, v152
	ds_bpermute_b32 v153, v213, v153
	ds_bpermute_b32 v154, v213, v154
	ds_bpermute_b32 v155, v213, v155
	ds_bpermute_b32 v150, v213, v150
	ds_bpermute_b32 v151, v213, v151
	ds_bpermute_b32 v148, v213, v148
	s_waitcnt lgkmcnt(7)
	ds_bpermute_b32 v149, v213, v149
	s_waitcnt lgkmcnt(0)
	v_cvt_f32_ubyte0_e32 v145, v196
	v_rcp_f32_e32 v145, v145
	v_cvt_f32_ubyte0_e32 v213, v192
	v_cvt_f32_ubyte1_e32 v216, v193
	v_cndmask_b32_e64 v145, v145, v203, s[38:39]
	v_mul_f32_e32 v145, v213, v145
	v_cvt_f32_ubyte1_e32 v213, v196
	v_rcp_f32_e32 v214, v213
	v_mul_f32_e32 v213, v126, v145
	v_cvt_f32_ubyte1_e32 v145, v192
	v_cndmask_b32_e64 v214, v214, v203, s[38:39]
	v_mul_f32_e32 v145, v145, v214
	v_cvt_f32_ubyte2_e32 v214, v196
	v_rcp_f32_e32 v215, v214
	v_mul_f32_e32 v214, v127, v145
	v_cvt_f32_ubyte2_e32 v145, v192
	v_cvt_f32_ubyte3_e32 v196, v196
	v_cndmask_b32_e64 v215, v215, v203, s[38:39]
	v_mul_f32_e32 v145, v145, v215
	v_rcp_f32_e32 v215, v196
	v_mul_f32_e32 v196, v128, v145
	v_cvt_f32_ubyte3_e32 v145, v192
	v_cndmask_b32_e64 v192, v215, v203, s[38:39]
	v_mul_f32_e32 v145, v145, v192
	v_cvt_f32_ubyte0_e32 v192, v197
	v_rcp_f32_e32 v192, v192
	v_mul_f32_e32 v215, v129, v145
	v_cvt_f32_ubyte0_e32 v145, v193
	v_cndmask_b32_e64 v192, v192, v203, s[38:39]
	v_mul_f32_e32 v145, v145, v192
	v_cvt_f32_ubyte1_e32 v192, v197
	v_rcp_f32_e32 v192, v192
	v_cvt_f32_ubyte2_e32 v217, v193
	v_cndmask_b32_e64 v192, v192, v203, s[38:39]
	v_mul_f32_e32 v192, v216, v192
	v_cvt_f32_ubyte2_e32 v216, v197
	v_rcp_f32_e32 v216, v216
	v_cvt_f32_ubyte3_e32 v197, v197
	s_and_b32 s1, s30, 0x300
	v_cndmask_b32_e64 v216, v216, v203, s[38:39]
	v_mul_f32_e32 v216, v217, v216
	v_rcp_f32_e32 v217, v197
	v_cvt_f32_ubyte3_e32 v193, v193
	v_lshl_add_u64 v[194:195], s[12:13], 0, v[194:195]
	s_lshl_b32 s30, s1, 1
	v_mul_f32_e32 v197, v124, v216
	v_cndmask_b32_e64 v216, v217, v203, s[38:39]
	v_lshl_add_u64 v[194:195], v[194:195], 0, s[30:31]
	v_mul_f32_e32 v193, v193, v216
	v_cndmask_b32_e64 v216, 0, 1, s[38:39]
	v_lshl_add_u64 v[194:195], v[194:195], 0, v[0:1]
	v_mul_f32_e32 v145, v122, v145
	v_mul_f32_e32 v192, v123, v192
	v_cmp_ne_u32_e64 s[40:41], 1, v216
	s_andn2_b64 vcc, exec, s[38:39]
	v_mul_f32_e32 v193, v125, v193
	s_cbranch_vccnz .LBB0_42
	v_cvt_pk_bf16_f32 v216, v213, v214
	v_cvt_pk_bf16_f32 v217, v196, v215
	v_cvt_pk_bf16_f32 v218, v145, v192
	v_cvt_pk_bf16_f32 v219, v197, v193
	v_bfe_u32 v164, v198, 2, 4
	v_and_b32_e32 v165, 15, v198
	v_sub_u32_e32 v164, v164, v165
	v_and_b32_e32 v165, 3, v198
	v_bfe_u32 v166, v198, 4, 2
	v_sub_u32_e32 v165, v165, v166
	v_lshlrev_b32_e32 v164, 11, v164
	v_lshl_add_u32 v164, v165, 4, v164
	v_ashrrev_i32_e32 v165, 31, v164
	v_and_b32_e32 v162, 3, v198
	v_bfe_u32 v166, v198, 2, 4
	v_lshl_add_u32 v162, v162, 4, v166
	v_lshlrev_b32_e32 v162, 2, v162
	v_lshl_add_u64 v[166:167], v[194:195], 0, v[164:165]
	ds_bpermute_b32 v168, v162, v216
	ds_bpermute_b32 v169, v162, v217
	ds_bpermute_b32 v170, v162, v218
	ds_bpermute_b32 v171, v162, v219
	s_branch .LBB0_43

; __device__ __forceinline__ unsigned cvtpk(float lo, float hi) { unsigned r; asm volatile("v_cvt_pk_bf16_f32 %0, %1, %2" : "=v"(r) : "v"(lo), "v"(hi)); return r; }
;     __device__ __forceinline__ void operator()(f32x4 (&acc)[2][2][4][2], const pg8::Unit& u, int wr, int wc, int fr, int fq) const {
;     ...
;             for (int m = 0; m < 4; ++m) {
;                 u16* op = hbuf + (size_t)(row0 + ai * 128 + m * 16) * DM + (u.pn & 3) * 256 + cin;
; #pragma unroll
;                 for (int bj = 0; bj < 2; ++bj) {
;                     f32x4 vv[2];
; #pragma unroll
;                     for (int n = 0; n < 2; ++n) {
;                         const unsigned a4 = ga[m][bj][n], b4 = gb[m][bj][n]; f32x4 v = acc[ai][bj][m][n];
; #pragma unroll
;                         for (int j = 0; j < 4; ++j) { const float ga_ = fmaxf((float)((a4 >> (8 * j)) & 255u), 1.f), gb_ = fmaxf((float)((b4 >> (8 * j)) & 255u), 1.f);
;                             v[j] *= last ? ga_ * (1.f / 255.f) : ga_ * __builtin_amdgcn_rcpf(gb_); }
;                         vv[n] = v; if (!last) acc[ai][bj][m][n] = v;
;                     }
;                     if (last) { u32x4 o = {cvtpk(vv[0][0], vv[0][1]), cvtpk(vv[0][2], vv[0][3]), cvtpk(vv[1][0], vv[1][1]), cvtpk(vv[1][2], vv[1][3])}; *(u32x4*)(op + bj * 128) = o; }
.LBB0_43:
	v_cvt_f32_ubyte0_e32 v145, v188
	v_rcp_f32_e32 v145, v145
	v_cvt_f32_ubyte0_e32 v192, v190
	v_cvt_f32_ubyte1_e32 v193, v188
	v_cndmask_b32_e64 v145, v145, v203, s[38:39]
	v_mul_f32_e32 v145, v192, v145
	v_max_f32_e32 v192, 1.0, v193
	v_rcp_f32_e32 v192, v192
	v_mul_f32_e32 v197, v94, v145
	v_cvt_f32_ubyte1_e32 v145, v190
	v_cndmask_b32_e64 v192, v192, v203, s[38:39]
	v_mul_f32_e32 v145, v145, v192
	v_cvt_f32_ubyte2_e32 v192, v188
	v_rcp_f32_e32 v192, v192
	v_cvt_f32_ubyte3_e32 v188, v188
	v_mul_f32_e32 v216, v95, v145
	v_cvt_f32_ubyte2_e32 v145, v190
	v_rcp_f32_e32 v188, v188
	v_cndmask_b32_e64 v192, v192, v203, s[38:39]
	v_mul_f32_e32 v145, v145, v192
	v_mul_f32_e32 v217, v96, v145
	v_cvt_f32_ubyte3_e32 v145, v190
	v_cndmask_b32_e64 v188, v188, v203, s[38:39]
	v_mul_f32_e32 v145, v145, v188
	v_cvt_f32_ubyte0_e32 v188, v189
	v_rcp_f32_e32 v188, v188
	v_mul_f32_e32 v218, v97, v145
	v_cvt_f32_ubyte0_e32 v145, v191
	v_cndmask_b32_e64 v188, v188, v203, s[38:39]
	v_mul_f32_e32 v145, v145, v188
	v_cvt_f32_ubyte1_e32 v188, v189
	v_rcp_f32_e32 v188, v188
	v_cvt_f32_ubyte1_e32 v190, v191
	v_cvt_f32_ubyte2_e32 v192, v191
	v_cndmask_b32_e64 v188, v188, v203, s[38:39]
	v_mul_f32_e32 v188, v190, v188
	v_cvt_f32_ubyte2_e32 v190, v189
	v_rcp_f32_e32 v190, v190
	v_cvt_f32_ubyte3_e32 v189, v189
	v_cndmask_b32_e64 v190, v190, v203, s[38:39]
	v_mul_f32_e32 v190, v192, v190
	v_rcp_f32_e32 v192, v189
	v_mul_f32_e32 v189, v92, v190
	v_cvt_f32_ubyte3_e32 v190, v191
	v_cndmask_b32_e64 v191, v192, v203, s[38:39]
	v_mul_f32_e32 v190, v190, v191
	v_mul_f32_e32 v145, v90, v145
	v_mul_f32_e32 v188, v91, v188
	s_and_b64 vcc, exec, s[40:41]
	v_mul_f32_e32 v190, v93, v190
	s_cbranch_vccnz .LBB0_45
	v_cvt_pk_bf16_f32 v220, v197, v216
	v_cvt_pk_bf16_f32 v221, v217, v218
	v_cvt_pk_bf16_f32 v222, v145, v188
	v_cvt_pk_bf16_f32 v223, v189, v190
	s_waitcnt lgkmcnt(0)
	global_store_dwordx4 v[166:167], v[168:171], off
	v_lshl_add_u64 v[166:167], v[194:195], 0, v[164:165]
	ds_bpermute_b32 v168, v162, v220
	ds_bpermute_b32 v169, v162, v221
	ds_bpermute_b32 v170, v162, v222
	ds_bpermute_b32 v171, v162, v223
	s_branch .LBB0_46

; __device__ __forceinline__ unsigned cvtpk(float lo, float hi) { unsigned r; asm volatile("v_cvt_pk_bf16_f32 %0, %1, %2" : "=v"(r) : "v"(lo), "v"(hi)); return r; }
;     __device__ __forceinline__ void operator()(f32x4 (&acc)[2][2][4][2], const pg8::Unit& u, int wr, int wc, int fr, int fq) const {
;     ...
;             for (int m = 0; m < 4; ++m) {
;                 u16* op = hbuf + (size_t)(row0 + ai * 128 + m * 16) * DM + (u.pn & 3) * 256 + cin;
; #pragma unroll
;                 for (int bj = 0; bj < 2; ++bj) {
;                     f32x4 vv[2];
; #pragma unroll
;                     for (int n = 0; n < 2; ++n) {
;                         const unsigned a4 = ga[m][bj][n], b4 = gb[m][bj][n]; f32x4 v = acc[ai][bj][m][n];
; #pragma unroll
;                         for (int j = 0; j < 4; ++j) { const float ga_ = fmaxf((float)((a4 >> (8 * j)) & 255u), 1.f), gb_ = fmaxf((float)((b4 >> (8 * j)) & 255u), 1.f);
;                             v[j] *= last ? ga_ * (1.f / 255.f) : ga_ * __builtin_amdgcn_rcpf(gb_); }
;                         vv[n] = v; if (!last) acc[ai][bj][m][n] = v;
;                     }
;                     if (last) { u32x4 o = {cvtpk(vv[0][0], vv[0][1]), cvtpk(vv[0][2], vv[0][3]), cvtpk(vv[1][0], vv[1][1]), cvtpk(vv[1][2], vv[1][3])}; *(u32x4*)(op + bj * 128) = o; }
.LBB0_46:
	v_cvt_f32_ubyte0_e32 v145, v184
	v_rcp_f32_e32 v145, v145
	v_cvt_f32_ubyte0_e32 v188, v182
	v_lshlrev_b64 v[186:187], 11, v[186:187]
	v_cndmask_b32_e64 v145, v145, v203, s[38:39]
	v_mul_f32_e32 v145, v188, v145
	v_cvt_f32_ubyte1_e32 v188, v184
	v_rcp_f32_e32 v188, v188
	v_mul_f32_e32 v219, v118, v145
	v_cvt_f32_ubyte1_e32 v145, v182
	v_cndmask_b32_e64 v188, v188, v203, s[38:39]
	v_mul_f32_e32 v145, v145, v188
	v_cvt_f32_ubyte2_e32 v188, v184
	v_rcp_f32_e32 v188, v188
	v_cvt_f32_ubyte3_e32 v184, v184
	v_mul_f32_e32 v220, v119, v145
	v_cvt_f32_ubyte2_e32 v145, v182
	v_rcp_f32_e32 v184, v184
	v_cndmask_b32_e64 v188, v188, v203, s[38:39]
	v_mul_f32_e32 v145, v145, v188
	v_mul_f32_e32 v221, v120, v145
	v_cvt_f32_ubyte3_e32 v145, v182
	v_cndmask_b32_e64 v182, v184, v203, s[38:39]
	v_mul_f32_e32 v145, v145, v182
	v_cvt_f32_ubyte0_e32 v182, v185
	v_rcp_f32_e32 v182, v182
	v_mul_f32_e32 v222, v121, v145
	v_cvt_f32_ubyte0_e32 v145, v183
	v_cndmask_b32_e64 v182, v182, v203, s[38:39]
	v_mul_f32_e32 v145, v145, v182
	v_cvt_f32_ubyte1_e32 v182, v185
	v_rcp_f32_e32 v182, v182
	v_cvt_f32_ubyte1_e32 v184, v183
	v_cvt_f32_ubyte2_e32 v188, v183
	v_cndmask_b32_e64 v182, v182, v203, s[38:39]
	v_mul_f32_e32 v182, v184, v182
	v_cvt_f32_ubyte2_e32 v184, v185
	v_cvt_f32_ubyte3_e32 v185, v185
	v_rcp_f32_e32 v184, v184
	v_rcp_f32_e32 v185, v185
	v_cvt_f32_ubyte3_e32 v183, v183
	v_lshl_add_u64 v[186:187], s[12:13], 0, v[186:187]
	v_cndmask_b32_e64 v184, v184, v203, s[38:39]
	v_cndmask_b32_e64 v185, v185, v203, s[38:39]
	v_lshl_add_u64 v[186:187], v[186:187], 0, s[30:31]
	v_mul_f32_e32 v184, v188, v184
	v_mul_f32_e32 v183, v183, v185
	v_lshl_add_u64 v[186:187], v[186:187], 0, v[0:1]
	v_mul_f32_e32 v145, v114, v145
	v_mul_f32_e32 v182, v115, v182
	v_mul_f32_e32 v184, v116, v184
	s_and_b64 vcc, exec, s[40:41]
	v_mul_f32_e32 v183, v117, v183
	s_cbranch_vccnz .LBB0_48
	v_cvt_pk_bf16_f32 v188, v219, v220
	v_cvt_pk_bf16_f32 v189, v221, v222
	v_cvt_pk_bf16_f32 v190, v145, v182
	v_cvt_pk_bf16_f32 v191, v184, v183
	s_waitcnt lgkmcnt(0)
	global_store_dwordx4 v[166:167], v[168:171], off offset:256
	v_lshl_add_u64 v[166:167], v[186:187], 0, v[164:165]
	ds_bpermute_b32 v168, v162, v188
	ds_bpermute_b32 v169, v162, v189
	ds_bpermute_b32 v170, v162, v190
	ds_bpermute_b32 v171, v162, v191
	s_branch .LBB0_49

; __device__ __forceinline__ unsigned cvtpk(float lo, float hi) { unsigned r; asm volatile("v_cvt_pk_bf16_f32 %0, %1, %2" : "=v"(r) : "v"(lo), "v"(hi)); return r; }
;     __device__ __forceinline__ void operator()(f32x4 (&acc)[2][2][4][2], const pg8::Unit& u, int wr, int wc, int fr, int fq) const {
;     ...
;             for (int m = 0; m < 4; ++m) {
;                 u16* op = hbuf + (size_t)(row0 + ai * 128 + m * 16) * DM + (u.pn & 3) * 256 + cin;
; #pragma unroll
;                 for (int bj = 0; bj < 2; ++bj) {
;                     f32x4 vv[2];
; #pragma unroll
;                     for (int n = 0; n < 2; ++n) {
;                         const unsigned a4 = ga[m][bj][n], b4 = gb[m][bj][n]; f32x4 v = acc[ai][bj][m][n];
; #pragma unroll
;                         for (int j = 0; j < 4; ++j) { const float ga_ = fmaxf((float)((a4 >> (8 * j)) & 255u), 1.f), gb_ = fmaxf((float)((b4 >> (8 * j)) & 255u), 1.f);
;                             v[j] *= last ? ga_ * (1.f / 255.f) : ga_ * __builtin_amdgcn_rcpf(gb_); }
;                         vv[n] = v; if (!last) acc[ai][bj][m][n] = v;
;                     }
;                     if (last) { u32x4 o = {cvtpk(vv[0][0], vv[0][1]), cvtpk(vv[0][2], vv[0][3]), cvtpk(vv[1][0], vv[1][1]), cvtpk(vv[1][2], vv[1][3])}; *(u32x4*)(op + bj * 128) = o; }
.LBB0_49:
	v_cvt_f32_ubyte0_e32 v145, v178
	v_rcp_f32_e32 v145, v145
	v_cvt_f32_ubyte0_e32 v182, v180
	v_cvt_f32_ubyte1_e32 v183, v178
	v_cndmask_b32_e64 v145, v145, v203, s[38:39]
	v_mul_f32_e32 v145, v182, v145
	v_max_f32_e32 v182, 1.0, v183
	v_rcp_f32_e32 v182, v182
	v_mul_f32_e32 v223, v86, v145
	v_cvt_f32_ubyte1_e32 v145, v180
	v_cndmask_b32_e64 v182, v182, v203, s[38:39]
	v_mul_f32_e32 v145, v145, v182
	v_cvt_f32_ubyte2_e32 v182, v178
	v_rcp_f32_e32 v182, v182
	v_cvt_f32_ubyte3_e32 v178, v178
	v_mul_f32_e32 v224, v87, v145
	v_cvt_f32_ubyte2_e32 v145, v180
	v_rcp_f32_e32 v178, v178
	v_cndmask_b32_e64 v182, v182, v203, s[38:39]
	v_mul_f32_e32 v145, v145, v182
	v_mul_f32_e32 v225, v88, v145
	v_cvt_f32_ubyte3_e32 v145, v180
	v_cndmask_b32_e64 v178, v178, v203, s[38:39]
	v_mul_f32_e32 v145, v145, v178
	v_cvt_f32_ubyte0_e32 v178, v179
	v_rcp_f32_e32 v178, v178
	v_mul_f32_e32 v226, v89, v145
	v_cvt_f32_ubyte0_e32 v145, v181
	v_cndmask_b32_e64 v178, v178, v203, s[38:39]
	v_mul_f32_e32 v145, v145, v178
	v_cvt_f32_ubyte1_e32 v178, v179
	v_rcp_f32_e32 v178, v178
	v_cvt_f32_ubyte1_e32 v180, v181
	v_cvt_f32_ubyte2_e32 v182, v181
	v_cndmask_b32_e64 v178, v178, v203, s[38:39]
	v_mul_f32_e32 v178, v180, v178
	v_cvt_f32_ubyte2_e32 v180, v179
	v_rcp_f32_e32 v180, v180
	v_cvt_f32_ubyte3_e32 v179, v179
	v_cndmask_b32_e64 v180, v180, v203, s[38:39]
	v_mul_f32_e32 v180, v182, v180
	v_rcp_f32_e32 v182, v179
	v_mul_f32_e32 v179, v84, v180
	v_cvt_f32_ubyte3_e32 v180, v181
	v_cndmask_b32_e64 v181, v182, v203, s[38:39]
	v_mul_f32_e32 v180, v180, v181
	v_mul_f32_e32 v145, v82, v145
	v_mul_f32_e32 v178, v83, v178
	s_and_b64 vcc, exec, s[40:41]
	v_mul_f32_e32 v180, v85, v180
	s_cbranch_vccnz .LBB0_51
	v_cvt_pk_bf16_f32 v182, v223, v224
	v_cvt_pk_bf16_f32 v183, v225, v226
	v_cvt_pk_bf16_f32 v184, v145, v178
	v_cvt_pk_bf16_f32 v185, v179, v180
	s_waitcnt lgkmcnt(0)
	global_store_dwordx4 v[166:167], v[168:171], off
	v_lshl_add_u64 v[166:167], v[186:187], 0, v[164:165]
	ds_bpermute_b32 v168, v162, v182
	ds_bpermute_b32 v169, v162, v183
	ds_bpermute_b32 v170, v162, v184
	ds_bpermute_b32 v171, v162, v185
	s_branch .LBB0_52

; __device__ __forceinline__ unsigned cvtpk(float lo, float hi) { unsigned r; asm volatile("v_cvt_pk_bf16_f32 %0, %1, %2" : "=v"(r) : "v"(lo), "v"(hi)); return r; }
;     __device__ __forceinline__ void operator()(f32x4 (&acc)[2][2][4][2], const pg8::Unit& u, int wr, int wc, int fr, int fq) const {
;     ...
;             for (int m = 0; m < 4; ++m) {
;                 u16* op = hbuf + (size_t)(row0 + ai * 128 + m * 16) * DM + (u.pn & 3) * 256 + cin;
; #pragma unroll
;                 for (int bj = 0; bj < 2; ++bj) {
;                     f32x4 vv[2];
; #pragma unroll
;                     for (int n = 0; n < 2; ++n) {
;                         const unsigned a4 = ga[m][bj][n], b4 = gb[m][bj][n]; f32x4 v = acc[ai][bj][m][n];
; #pragma unroll
;                         for (int j = 0; j < 4; ++j) { const float ga_ = fmaxf((float)((a4 >> (8 * j)) & 255u), 1.f), gb_ = fmaxf((float)((b4 >> (8 * j)) & 255u), 1.f);
;                             v[j] *= last ? ga_ * (1.f / 255.f) : ga_ * __builtin_amdgcn_rcpf(gb_); }
;                         vv[n] = v; if (!last) acc[ai][bj][m][n] = v;
;                     }
;                     if (last) { u32x4 o = {cvtpk(vv[0][0], vv[0][1]), cvtpk(vv[0][2], vv[0][3]), cvtpk(vv[1][0], vv[1][1]), cvtpk(vv[1][2], vv[1][3])}; *(u32x4*)(op + bj * 128) = o; }
.LBB0_52:
	v_cvt_f32_ubyte0_e32 v145, v174
	v_rcp_f32_e32 v145, v145
	v_cvt_f32_ubyte0_e32 v178, v172
	v_lshlrev_b64 v[176:177], 11, v[176:177]
	v_cndmask_b32_e64 v145, v145, v203, s[38:39]
	v_mul_f32_e32 v145, v178, v145
	v_cvt_f32_ubyte1_e32 v178, v174
	v_rcp_f32_e32 v178, v178
	v_mul_f32_e32 v227, v110, v145
	v_cvt_f32_ubyte1_e32 v145, v172
	v_cndmask_b32_e64 v178, v178, v203, s[38:39]
	v_mul_f32_e32 v145, v145, v178
	v_cvt_f32_ubyte2_e32 v178, v174
	v_rcp_f32_e32 v178, v178
	v_cvt_f32_ubyte3_e32 v174, v174
	v_mul_f32_e32 v228, v111, v145
	v_cvt_f32_ubyte2_e32 v145, v172
	v_rcp_f32_e32 v174, v174
	v_cndmask_b32_e64 v178, v178, v203, s[38:39]
	v_mul_f32_e32 v145, v145, v178
	v_mul_f32_e32 v229, v112, v145
	v_cvt_f32_ubyte3_e32 v145, v172
	v_cndmask_b32_e64 v172, v174, v203, s[38:39]
	v_mul_f32_e32 v145, v145, v172
	v_cvt_f32_ubyte0_e32 v172, v175
	v_rcp_f32_e32 v172, v172
	v_mul_f32_e32 v230, v113, v145
	v_cvt_f32_ubyte0_e32 v145, v173
	v_cndmask_b32_e64 v172, v172, v203, s[38:39]
	v_mul_f32_e32 v145, v145, v172
	v_cvt_f32_ubyte1_e32 v172, v175
	v_rcp_f32_e32 v172, v172
	v_cvt_f32_ubyte1_e32 v174, v173
	v_cvt_f32_ubyte2_e32 v178, v173
	v_cndmask_b32_e64 v172, v172, v203, s[38:39]
	v_mul_f32_e32 v172, v174, v172
	v_cvt_f32_ubyte2_e32 v174, v175
	v_cvt_f32_ubyte3_e32 v175, v175
	v_rcp_f32_e32 v174, v174
	v_rcp_f32_e32 v175, v175
	v_cvt_f32_ubyte3_e32 v173, v173
	v_lshl_add_u64 v[176:177], s[12:13], 0, v[176:177]
	v_cndmask_b32_e64 v174, v174, v203, s[38:39]
	v_cndmask_b32_e64 v175, v175, v203, s[38:39]
	v_lshl_add_u64 v[176:177], v[176:177], 0, s[30:31]
	v_mul_f32_e32 v174, v178, v174
	v_mul_f32_e32 v173, v173, v175
	v_lshl_add_u64 v[176:177], v[176:177], 0, v[0:1]
	v_mul_f32_e32 v145, v106, v145
	v_mul_f32_e32 v172, v107, v172
	v_mul_f32_e32 v174, v108, v174
	s_and_b64 vcc, exec, s[40:41]
	v_mul_f32_e32 v173, v109, v173
	s_cbranch_vccnz .LBB0_54
	v_cvt_pk_bf16_f32 v178, v227, v228
	v_cvt_pk_bf16_f32 v179, v229, v230
	v_cvt_pk_bf16_f32 v180, v145, v172
	v_cvt_pk_bf16_f32 v181, v174, v173
	s_waitcnt lgkmcnt(0)
	global_store_dwordx4 v[166:167], v[168:171], off offset:256
	v_lshl_add_u64 v[166:167], v[176:177], 0, v[164:165]
	ds_bpermute_b32 v168, v162, v178
	ds_bpermute_b32 v169, v162, v179
	ds_bpermute_b32 v170, v162, v180
	ds_bpermute_b32 v171, v162, v181
	s_branch .LBB0_55

; __device__ __forceinline__ unsigned cvtpk(float lo, float hi) { unsigned r; asm volatile("v_cvt_pk_bf16_f32 %0, %1, %2" : "=v"(r) : "v"(lo), "v"(hi)); return r; }
;     __device__ __forceinline__ void operator()(f32x4 (&acc)[2][2][4][2], const pg8::Unit& u, int wr, int wc, int fr, int fq) const {
;     ...
;             for (int m = 0; m < 4; ++m) {
;                 u16* op = hbuf + (size_t)(row0 + ai * 128 + m * 16) * DM + (u.pn & 3) * 256 + cin;
; #pragma unroll
;                 for (int bj = 0; bj < 2; ++bj) {
;                     f32x4 vv[2];
; #pragma unroll
;                     for (int n = 0; n < 2; ++n) {
;                         const unsigned a4 = ga[m][bj][n], b4 = gb[m][bj][n]; f32x4 v = acc[ai][bj][m][n];
; #pragma unroll
;                         for (int j = 0; j < 4; ++j) { const float ga_ = fmaxf((float)((a4 >> (8 * j)) & 255u), 1.f), gb_ = fmaxf((float)((b4 >> (8 * j)) & 255u), 1.f);
;                             v[j] *= last ? ga_ * (1.f / 255.f) : ga_ * __builtin_amdgcn_rcpf(gb_); }
;                         vv[n] = v; if (!last) acc[ai][bj][m][n] = v;
;                     }
;                     if (last) { u32x4 o = {cvtpk(vv[0][0], vv[0][1]), cvtpk(vv[0][2], vv[0][3]), cvtpk(vv[1][0], vv[1][1]), cvtpk(vv[1][2], vv[1][3])}; *(u32x4*)(op + bj * 128) = o; }
.LBB0_55:
	v_cvt_f32_ubyte0_e32 v145, v158
	v_rcp_f32_e32 v145, v145
	v_cvt_f32_ubyte0_e32 v172, v160
	v_cvt_f32_ubyte1_e32 v173, v158
	v_cndmask_b32_e64 v145, v145, v203, s[38:39]
	v_mul_f32_e32 v145, v172, v145
	v_max_f32_e32 v172, 1.0, v173
	v_rcp_f32_e32 v172, v172
	v_mul_f32_e32 v231, v78, v145
	v_cvt_f32_ubyte1_e32 v145, v160
	v_cndmask_b32_e64 v172, v172, v203, s[38:39]
	v_mul_f32_e32 v145, v145, v172
	v_cvt_f32_ubyte2_e32 v172, v158
	v_rcp_f32_e32 v172, v172
	v_cvt_f32_ubyte3_e32 v158, v158
	v_mul_f32_e32 v232, v79, v145
	v_cvt_f32_ubyte2_e32 v145, v160
	v_rcp_f32_e32 v158, v158
	v_cndmask_b32_e64 v172, v172, v203, s[38:39]
	v_mul_f32_e32 v145, v145, v172
	v_mul_f32_e32 v233, v80, v145
	v_cvt_f32_ubyte3_e32 v145, v160
	v_cndmask_b32_e64 v158, v158, v203, s[38:39]
	v_mul_f32_e32 v145, v145, v158
	v_cvt_f32_ubyte0_e32 v158, v159
	v_rcp_f32_e32 v158, v158
	v_mul_f32_e32 v234, v81, v145
	v_cvt_f32_ubyte0_e32 v145, v161
	v_cndmask_b32_e64 v158, v158, v203, s[38:39]
	v_mul_f32_e32 v145, v145, v158
	v_cvt_f32_ubyte1_e32 v158, v159
	v_rcp_f32_e32 v158, v158
	v_cvt_f32_ubyte1_e32 v160, v161
	v_cvt_f32_ubyte2_e32 v172, v161
	v_cndmask_b32_e64 v158, v158, v203, s[38:39]
	v_mul_f32_e32 v158, v160, v158
	v_cvt_f32_ubyte2_e32 v160, v159
	v_rcp_f32_e32 v160, v160
	v_cvt_f32_ubyte3_e32 v159, v159
	v_cndmask_b32_e64 v160, v160, v203, s[38:39]
	v_mul_f32_e32 v160, v172, v160
	v_rcp_f32_e32 v172, v159
	v_mul_f32_e32 v159, v76, v160
	v_cvt_f32_ubyte3_e32 v160, v161
	v_cndmask_b32_e64 v161, v172, v203, s[38:39]
	v_mul_f32_e32 v160, v160, v161
	v_mul_f32_e32 v145, v74, v145
	v_mul_f32_e32 v158, v75, v158
	s_and_b64 vcc, exec, s[40:41]
	v_mul_f32_e32 v160, v77, v160
	s_cbranch_vccnz .LBB0_57
	v_cvt_pk_bf16_f32 v172, v231, v232
	v_cvt_pk_bf16_f32 v173, v233, v234
	v_cvt_pk_bf16_f32 v174, v145, v158
	v_cvt_pk_bf16_f32 v175, v159, v160
	s_waitcnt lgkmcnt(0)
	global_store_dwordx4 v[166:167], v[168:171], off
	v_lshl_add_u64 v[166:167], v[176:177], 0, v[164:165]
	ds_bpermute_b32 v168, v162, v172
	ds_bpermute_b32 v169, v162, v173
	ds_bpermute_b32 v170, v162, v174
	ds_bpermute_b32 v171, v162, v175
	s_branch .LBB0_58

; __device__ __forceinline__ unsigned cvtpk(float lo, float hi) { unsigned r; asm volatile("v_cvt_pk_bf16_f32 %0, %1, %2" : "=v"(r) : "v"(lo), "v"(hi)); return r; }
;     __device__ __forceinline__ void operator()(f32x4 (&acc)[2][2][4][2], const pg8::Unit& u, int wr, int wc, int fr, int fq) const {
;     ...
;             for (int m = 0; m < 4; ++m) {
;                 u16* op = hbuf + (size_t)(row0 + ai * 128 + m * 16) * DM + (u.pn & 3) * 256 + cin;
; #pragma unroll
;                 for (int bj = 0; bj < 2; ++bj) {
;                     f32x4 vv[2];
; #pragma unroll
;                     for (int n = 0; n < 2; ++n) {
;                         const unsigned a4 = ga[m][bj][n], b4 = gb[m][bj][n]; f32x4 v = acc[ai][bj][m][n];
; #pragma unroll
;                         for (int j = 0; j < 4; ++j) { const float ga_ = fmaxf((float)((a4 >> (8 * j)) & 255u), 1.f), gb_ = fmaxf((float)((b4 >> (8 * j)) & 255u), 1.f);
;                             v[j] *= last ? ga_ * (1.f / 255.f) : ga_ * __builtin_amdgcn_rcpf(gb_); }
;                         vv[n] = v; if (!last) acc[ai][bj][m][n] = v;
;                     }
;                     if (last) { u32x4 o = {cvtpk(vv[0][0], vv[0][1]), cvtpk(vv[0][2], vv[0][3]), cvtpk(vv[1][0], vv[1][1]), cvtpk(vv[1][2], vv[1][3])}; *(u32x4*)(op + bj * 128) = o; }
.LBB0_58:
	v_cvt_f32_ubyte0_e32 v145, v154
	v_rcp_f32_e32 v145, v145
	v_cvt_f32_ubyte0_e32 v158, v152
	v_lshlrev_b64 v[156:157], 11, v[156:157]
	v_cndmask_b32_e64 v145, v145, v203, s[38:39]
	v_mul_f32_e32 v145, v158, v145
	v_cvt_f32_ubyte1_e32 v158, v154
	v_rcp_f32_e32 v158, v158
	v_mul_f32_e32 v235, v102, v145
	v_cvt_f32_ubyte1_e32 v145, v152
	v_cndmask_b32_e64 v158, v158, v203, s[38:39]
	v_mul_f32_e32 v145, v145, v158
	v_cvt_f32_ubyte2_e32 v158, v154
	v_rcp_f32_e32 v158, v158
	v_cvt_f32_ubyte3_e32 v154, v154
	v_mul_f32_e32 v236, v103, v145
	v_cvt_f32_ubyte2_e32 v145, v152
	v_rcp_f32_e32 v154, v154
	v_cndmask_b32_e64 v158, v158, v203, s[38:39]
	v_mul_f32_e32 v145, v145, v158
	v_mul_f32_e32 v237, v104, v145
	v_cvt_f32_ubyte3_e32 v145, v152
	v_cndmask_b32_e64 v152, v154, v203, s[38:39]
	v_mul_f32_e32 v145, v145, v152
	v_cvt_f32_ubyte0_e32 v152, v155
	v_rcp_f32_e32 v152, v152
	v_mul_f32_e32 v238, v105, v145
	v_cvt_f32_ubyte0_e32 v145, v153
	v_cndmask_b32_e64 v152, v152, v203, s[38:39]
	v_mul_f32_e32 v145, v145, v152
	v_cvt_f32_ubyte1_e32 v152, v155
	v_rcp_f32_e32 v152, v152
	v_cvt_f32_ubyte1_e32 v154, v153
	v_cvt_f32_ubyte2_e32 v158, v153
	v_cndmask_b32_e64 v152, v152, v203, s[38:39]
	v_mul_f32_e32 v152, v154, v152
	v_cvt_f32_ubyte2_e32 v154, v155
	v_cvt_f32_ubyte3_e32 v155, v155
	v_rcp_f32_e32 v154, v154
	v_rcp_f32_e32 v155, v155
	v_cvt_f32_ubyte3_e32 v153, v153
	v_lshl_add_u64 v[156:157], s[12:13], 0, v[156:157]
	v_cndmask_b32_e64 v154, v154, v203, s[38:39]
	v_cndmask_b32_e64 v155, v155, v203, s[38:39]
	v_lshl_add_u64 v[156:157], v[156:157], 0, s[30:31]
	v_mul_f32_e32 v154, v158, v154
	v_mul_f32_e32 v153, v153, v155
	v_lshl_add_u64 v[156:157], v[156:157], 0, v[0:1]
	v_mul_f32_e32 v145, v98, v145
	v_mul_f32_e32 v152, v99, v152
	v_mul_f32_e32 v154, v100, v154
	s_and_b64 vcc, exec, s[40:41]
	v_mul_f32_e32 v153, v101, v153
	s_cbranch_vccnz .LBB0_60
	v_cvt_pk_bf16_f32 v158, v235, v236
	v_cvt_pk_bf16_f32 v159, v237, v238
	v_cvt_pk_bf16_f32 v160, v145, v152
	v_cvt_pk_bf16_f32 v161, v154, v153
	s_waitcnt lgkmcnt(0)
	global_store_dwordx4 v[166:167], v[168:171], off offset:256
	v_lshl_add_u64 v[166:167], v[156:157], 0, v[164:165]
	ds_bpermute_b32 v168, v162, v158
	ds_bpermute_b32 v169, v162, v159
	ds_bpermute_b32 v170, v162, v160
	ds_bpermute_b32 v171, v162, v161
	s_branch .LBB0_61

; __device__ __forceinline__ unsigned cvtpk(float lo, float hi) { unsigned r; asm volatile("v_cvt_pk_bf16_f32 %0, %1, %2" : "=v"(r) : "v"(lo), "v"(hi)); return r; }
;     __device__ __forceinline__ void operator()(f32x4 (&acc)[2][2][4][2], const pg8::Unit& u, int wr, int wc, int fr, int fq) const {
;     ...
;             for (int m = 0; m < 4; ++m) {
;                 u16* op = hbuf + (size_t)(row0 + ai * 128 + m * 16) * DM + (u.pn & 3) * 256 + cin;
; #pragma unroll
;                 for (int bj = 0; bj < 2; ++bj) {
;                     f32x4 vv[2];
; #pragma unroll
;                     for (int n = 0; n < 2; ++n) {
;                         const unsigned a4 = ga[m][bj][n], b4 = gb[m][bj][n]; f32x4 v = acc[ai][bj][m][n];
; #pragma unroll
;                         for (int j = 0; j < 4; ++j) { const float ga_ = fmaxf((float)((a4 >> (8 * j)) & 255u), 1.f), gb_ = fmaxf((float)((b4 >> (8 * j)) & 255u), 1.f);
;                             v[j] *= last ? ga_ * (1.f / 255.f) : ga_ * __builtin_amdgcn_rcpf(gb_); }
;                         vv[n] = v; if (!last) acc[ai][bj][m][n] = v;
;                     }
;                     if (last) { u32x4 o = {cvtpk(vv[0][0], vv[0][1]), cvtpk(vv[0][2], vv[0][3]), cvtpk(vv[1][0], vv[1][1]), cvtpk(vv[1][2], vv[1][3])}; *(u32x4*)(op + bj * 128) = o; }
.LBB0_61:
	v_cvt_f32_ubyte0_e32 v145, v148
	v_rcp_f32_e32 v145, v145
	v_cvt_f32_ubyte0_e32 v152, v150
	v_cvt_f32_ubyte1_e32 v153, v148
	v_cndmask_b32_e64 v145, v145, v203, s[38:39]
	v_mul_f32_e32 v145, v152, v145
	v_max_f32_e32 v152, 1.0, v153
	v_rcp_f32_e32 v152, v152
	v_mul_f32_e32 v239, v70, v145
	v_cvt_f32_ubyte1_e32 v145, v150
	v_cndmask_b32_e64 v152, v152, v203, s[38:39]
	v_mul_f32_e32 v145, v145, v152
	v_cvt_f32_ubyte2_e32 v152, v148
	v_rcp_f32_e32 v152, v152
	v_cvt_f32_ubyte3_e32 v148, v148
	v_mul_f32_e32 v240, v71, v145
	v_cvt_f32_ubyte2_e32 v145, v150
	v_rcp_f32_e32 v148, v148
	v_cndmask_b32_e64 v152, v152, v203, s[38:39]
	v_mul_f32_e32 v145, v145, v152
	v_mul_f32_e32 v241, v72, v145
	v_cvt_f32_ubyte3_e32 v145, v150
	v_cndmask_b32_e64 v148, v148, v203, s[38:39]
	v_mul_f32_e32 v145, v145, v148
	v_cvt_f32_ubyte0_e32 v148, v149
	v_rcp_f32_e32 v148, v148
	v_mul_f32_e32 v242, v73, v145
	v_cvt_f32_ubyte0_e32 v145, v151
	v_cndmask_b32_e64 v148, v148, v203, s[38:39]
	v_mul_f32_e32 v145, v145, v148
	v_cvt_f32_ubyte1_e32 v148, v149
	v_rcp_f32_e32 v148, v148
	v_cvt_f32_ubyte1_e32 v150, v151
	v_cvt_f32_ubyte2_e32 v152, v151
	v_cndmask_b32_e64 v148, v148, v203, s[38:39]
	v_mul_f32_e32 v148, v150, v148
	v_cvt_f32_ubyte2_e32 v150, v149
	v_rcp_f32_e32 v150, v150
	v_cvt_f32_ubyte3_e32 v149, v149
	v_cndmask_b32_e64 v150, v150, v203, s[38:39]
	v_mul_f32_e32 v150, v152, v150
	v_rcp_f32_e32 v152, v149
	v_mul_f32_e32 v149, v68, v150
	v_cvt_f32_ubyte3_e32 v150, v151
	v_cndmask_b32_e64 v151, v152, v203, s[38:39]
	v_mul_f32_e32 v150, v150, v151
	v_mul_f32_e32 v145, v66, v145
	v_mul_f32_e32 v148, v67, v148
	s_and_b64 vcc, exec, s[40:41]
	v_mul_f32_e32 v150, v69, v150
	s_cbranch_vccnz .LBB0_63
	v_cvt_pk_bf16_f32 v152, v239, v240
	v_cvt_pk_bf16_f32 v153, v241, v242
	v_cvt_pk_bf16_f32 v154, v145, v148
	v_cvt_pk_bf16_f32 v155, v149, v150
	s_waitcnt lgkmcnt(0)
	global_store_dwordx4 v[166:167], v[168:171], off
	v_lshl_add_u64 v[166:167], v[156:157], 0, v[164:165]
	ds_bpermute_b32 v168, v162, v152
	ds_bpermute_b32 v169, v162, v153
	ds_bpermute_b32 v170, v162, v154
	ds_bpermute_b32 v171, v162, v155
	s_branch .LBB0_64

; __device__ __forceinline__ unsigned cvtpk(float lo, float hi) { unsigned r; asm volatile("v_cvt_pk_bf16_f32 %0, %1, %2" : "=v"(r) : "v"(lo), "v"(hi)); return r; }
;     __device__ __forceinline__ void operator()(f32x4 (&acc)[2][2][4][2], const pg8::Unit& u, int wr, int wc, int fr, int fq) const {
;     ...
;         for (int ai = 0; ai < 2; ++ai) {
;             u32x2 ga[4][2], gb[4][2];
; #pragma unroll
;             for (int m = 0; m < 4; ++m) {
;                 const unsigned char* gp = gq + (size_t)(row0 + ai * 128 + m * 16) * 4096 + u.pn * 256 + cin;
; #pragma unroll
;                 for (int bj = 0; bj < 2; ++bj) { ga[m][bj] = *(const u32x2*)(gp + bj * 128);
;                     gb[m][bj] = last ? (u32x2){0x01010101u, 0x01010101u} : *(const u32x2*)(gp + 1024 + bj * 128); }
;             }
; #pragma unroll
;             for (int m = 0; m < 4; ++m) {
;                 u16* op = hbuf + (size_t)(row0 + ai * 128 + m * 16) * DM + (u.pn & 3) * 256 + cin;
; #pragma unroll
;                 for (int bj = 0; bj < 2; ++bj) {
;                     f32x4 vv[2];
; #pragma unroll
;                     for (int n = 0; n < 2; ++n) {
;                         const unsigned a4 = ga[m][bj][n], b4 = gb[m][bj][n]; f32x4 v = acc[ai][bj][m][n];
; #pragma unroll
;                         for (int j = 0; j < 4; ++j) { const float ga_ = fmaxf((float)((a4 >> (8 * j)) & 255u), 1.f), gb_ = fmaxf((float)((b4 >> (8 * j)) & 255u), 1.f);
;                             v[j] *= last ? ga_ * (1.f / 255.f) : ga_ * __builtin_amdgcn_rcpf(gb_); }
;                         vv[n] = v; if (!last) acc[ai][bj][m][n] = v;
;                     }
;                     if (last) { u32x4 o = {cvtpk(vv[0][0], vv[0][1]), cvtpk(vv[0][2], vv[0][3]), cvtpk(vv[1][0], vv[1][1]), cvtpk(vv[1][2], vv[1][3])}; *(u32x4*)(op + bj * 128) = o; }
.LBB0_80:
	s_waitcnt vmcnt(0)
	v_and_b32_e32 v243, 15, v198
	v_bfe_u32 v244, v198, 4, 2
	v_lshl_or_b32 v243, v243, 2, v244
	v_lshlrev_b32_e32 v243, 2, v243
	ds_bpermute_b32 v188, v243, v188
	ds_bpermute_b32 v189, v243, v189
	ds_bpermute_b32 v192, v243, v192
	ds_bpermute_b32 v193, v243, v193
	ds_bpermute_b32 v186, v243, v186
	ds_bpermute_b32 v187, v243, v187
	ds_bpermute_b32 v184, v243, v184
	ds_bpermute_b32 v185, v243, v185
	ds_bpermute_b32 v178, v243, v178
	ds_bpermute_b32 v179, v243, v179
	ds_bpermute_b32 v180, v243, v180
	ds_bpermute_b32 v181, v243, v181
	ds_bpermute_b32 v176, v243, v176
	ds_bpermute_b32 v177, v243, v177
	ds_bpermute_b32 v174, v243, v174
	s_waitcnt lgkmcnt(7)
	ds_bpermute_b32 v175, v243, v175
	ds_bpermute_b32 v158, v243, v158
	ds_bpermute_b32 v159, v243, v159
	ds_bpermute_b32 v160, v243, v160
	ds_bpermute_b32 v161, v243, v161
	ds_bpermute_b32 v156, v243, v156
	ds_bpermute_b32 v157, v243, v157
	ds_bpermute_b32 v154, v243, v154
	s_waitcnt lgkmcnt(7)
	ds_bpermute_b32 v155, v243, v155
	ds_bpermute_b32 v148, v243, v148
	ds_bpermute_b32 v149, v243, v149
	ds_bpermute_b32 v150, v243, v150
	ds_bpermute_b32 v151, v243, v151
	ds_bpermute_b32 v146, v243, v146
	ds_bpermute_b32 v147, v243, v147
	ds_bpermute_b32 v144, v243, v144
	s_waitcnt lgkmcnt(7)
	ds_bpermute_b32 v145, v243, v145
	s_waitcnt lgkmcnt(0)
	v_cvt_f32_ubyte0_e32 v194, v192
	v_rcp_f32_e32 v194, v194
	v_cvt_f32_ubyte0_e32 v195, v188
	v_cvt_f32_ubyte1_e32 v243, v188
	v_cndmask_b32_e64 v194, v194, v203, s[38:39]
	v_mul_f32_e32 v194, v195, v194
	v_cvt_f32_ubyte1_e32 v195, v192
	v_rcp_f32_e32 v195, v195
	v_cvt_f32_ubyte2_e32 v244, v188
	v_cndmask_b32_e64 v195, v195, v203, s[38:39]
	v_mul_f32_e32 v195, v243, v195
	v_cvt_f32_ubyte2_e32 v243, v192
	v_rcp_f32_e32 v243, v243
	v_cvt_f32_ubyte3_e32 v192, v192
	v_cvt_f32_ubyte3_e32 v188, v188
	v_cndmask_b32_e64 v243, v243, v203, s[38:39]
	v_mul_f32_e32 v243, v244, v243
	v_rcp_f32_e32 v244, v192
	v_mul_f32_e32 v192, v64, v243
	v_cvt_f32_ubyte1_e32 v245, v189
	v_cndmask_b32_e64 v243, v244, v203, s[38:39]
	v_mul_f32_e32 v188, v188, v243
	v_cvt_f32_ubyte0_e32 v243, v193
	v_rcp_f32_e32 v243, v243
	v_cvt_f32_ubyte0_e32 v244, v189
	v_cndmask_b32_e64 v243, v243, v203, s[38:39]
	v_mul_f32_e32 v243, v244, v243
	v_cvt_f32_ubyte1_e32 v244, v193
	v_rcp_f32_e32 v244, v244
	v_cvt_f32_ubyte2_e32 v246, v189
	v_lshlrev_b64 v[190:191], 11, v[190:191]
	v_cndmask_b32_e64 v244, v244, v203, s[38:39]
	v_mul_f32_e32 v244, v245, v244
	v_cvt_f32_ubyte2_e32 v245, v193
	v_rcp_f32_e32 v245, v245
	v_cvt_f32_ubyte3_e32 v193, v193
	v_cvt_f32_ubyte3_e32 v189, v189
	v_cndmask_b32_e64 v245, v245, v203, s[38:39]
	v_mul_f32_e32 v245, v246, v245
	v_rcp_f32_e32 v246, v193
	v_lshl_add_u64 v[190:191], s[12:13], 0, v[190:191]
	v_mul_f32_e32 v193, v60, v245
	v_cndmask_b32_e64 v245, v246, v203, s[38:39]
	v_lshl_add_u64 v[190:191], v[190:191], 0, s[30:31]
	v_mul_f32_e32 v189, v189, v245
	v_lshl_add_u64 v[190:191], v[190:191], 0, v[0:1]
	v_mul_f32_e32 v194, v62, v194
	v_mul_f32_e32 v195, v63, v195
	v_mul_f32_e32 v188, v65, v188
	v_mul_f32_e32 v243, v58, v243
	v_mul_f32_e32 v244, v59, v244
	s_and_b64 vcc, exec, s[40:41]
	v_mul_f32_e32 v189, v61, v189
	s_cbranch_vccnz .LBB0_82
	v_cvt_pk_bf16_f32 v246, v194, v195
	v_cvt_pk_bf16_f32 v247, v192, v188
	v_cvt_pk_bf16_f32 v248, v243, v244
	v_cvt_pk_bf16_f32 v249, v193, v189
	s_waitcnt lgkmcnt(0)
	global_store_dwordx4 v[166:167], v[168:171], off offset:256
	v_lshl_add_u64 v[166:167], v[190:191], 0, v[164:165]
	ds_bpermute_b32 v168, v162, v246
	ds_bpermute_b32 v169, v162, v247
	ds_bpermute_b32 v170, v162, v248
	ds_bpermute_b32 v171, v162, v249
	s_branch .LBB0_83

; __device__ __forceinline__ unsigned cvtpk(float lo, float hi) { unsigned r; asm volatile("v_cvt_pk_bf16_f32 %0, %1, %2" : "=v"(r) : "v"(lo), "v"(hi)); return r; }
;     __device__ __forceinline__ void operator()(f32x4 (&acc)[2][2][4][2], const pg8::Unit& u, int wr, int wc, int fr, int fq) const {
;     ...
;             for (int m = 0; m < 4; ++m) {
;                 u16* op = hbuf + (size_t)(row0 + ai * 128 + m * 16) * DM + (u.pn & 3) * 256 + cin;
; #pragma unroll
;                 for (int bj = 0; bj < 2; ++bj) {
;                     f32x4 vv[2];
; #pragma unroll
;                     for (int n = 0; n < 2; ++n) {
;                         const unsigned a4 = ga[m][bj][n], b4 = gb[m][bj][n]; f32x4 v = acc[ai][bj][m][n];
; #pragma unroll
;                         for (int j = 0; j < 4; ++j) { const float ga_ = fmaxf((float)((a4 >> (8 * j)) & 255u), 1.f), gb_ = fmaxf((float)((b4 >> (8 * j)) & 255u), 1.f);
;                             v[j] *= last ? ga_ * (1.f / 255.f) : ga_ * __builtin_amdgcn_rcpf(gb_); }
;                         vv[n] = v; if (!last) acc[ai][bj][m][n] = v;
;                     }
;                     if (last) { u32x4 o = {cvtpk(vv[0][0], vv[0][1]), cvtpk(vv[0][2], vv[0][3]), cvtpk(vv[1][0], vv[1][1]), cvtpk(vv[1][2], vv[1][3])}; *(u32x4*)(op + bj * 128) = o; }
.LBB0_83:
	v_cvt_f32_ubyte0_e32 v189, v184
	v_rcp_f32_e32 v189, v189
	v_cvt_f32_ubyte0_e32 v193, v186
	v_cvt_f32_ubyte1_e32 v243, v184
	v_cndmask_b32_e64 v189, v189, v203, s[38:39]
	v_mul_f32_e32 v189, v193, v189
	v_max_f32_e32 v193, 1.0, v243
	v_rcp_f32_e32 v193, v193
	v_cvt_f32_ubyte1_e32 v243, v186
	v_cvt_f32_ubyte2_e32 v244, v186
	v_cndmask_b32_e64 v193, v193, v203, s[38:39]
	v_mul_f32_e32 v193, v243, v193
	v_cvt_f32_ubyte2_e32 v243, v184
	v_rcp_f32_e32 v243, v243
	v_cvt_f32_ubyte3_e32 v184, v184
	v_cndmask_b32_e64 v243, v243, v203, s[38:39]
	v_mul_f32_e32 v243, v244, v243
	v_rcp_f32_e32 v244, v184
	v_cvt_f32_ubyte3_e32 v186, v186
	v_mul_f32_e32 v184, v32, v243
	v_cndmask_b32_e64 v243, v244, v203, s[38:39]
	v_mul_f32_e32 v186, v186, v243
	v_cvt_f32_ubyte0_e32 v243, v185
	v_rcp_f32_e32 v243, v243
	v_cvt_f32_ubyte0_e32 v244, v187
	v_cvt_f32_ubyte1_e32 v245, v187
	v_cndmask_b32_e64 v243, v243, v203, s[38:39]
	v_mul_f32_e32 v243, v244, v243
	v_cvt_f32_ubyte1_e32 v244, v185
	v_rcp_f32_e32 v244, v244
	v_cvt_f32_ubyte2_e32 v246, v187
	v_cndmask_b32_e64 v244, v244, v203, s[38:39]
	v_mul_f32_e32 v244, v245, v244
	v_cvt_f32_ubyte2_e32 v245, v185
	v_rcp_f32_e32 v245, v245
	v_cvt_f32_ubyte3_e32 v185, v185
	v_cvt_f32_ubyte3_e32 v187, v187
	v_cndmask_b32_e64 v245, v245, v203, s[38:39]
	v_mul_f32_e32 v245, v246, v245
	v_rcp_f32_e32 v246, v185
	v_mul_f32_e32 v185, v28, v245
	v_mul_f32_e32 v189, v30, v189
	v_cndmask_b32_e64 v245, v246, v203, s[38:39]
	v_mul_f32_e32 v187, v187, v245
	v_mul_f32_e32 v193, v31, v193
	v_mul_f32_e32 v186, v33, v186
	v_mul_f32_e32 v243, v26, v243
	v_mul_f32_e32 v244, v27, v244
	s_and_b64 vcc, exec, s[40:41]
	v_mul_f32_e32 v187, v29, v187
	s_cbranch_vccnz .LBB0_85
	v_cvt_pk_bf16_f32 v246, v189, v193
	v_cvt_pk_bf16_f32 v247, v184, v186
	v_cvt_pk_bf16_f32 v248, v243, v244
	v_cvt_pk_bf16_f32 v249, v185, v187
	s_waitcnt lgkmcnt(0)
	global_store_dwordx4 v[166:167], v[168:171], off
	v_lshl_add_u64 v[166:167], v[190:191], 0, v[164:165]
	ds_bpermute_b32 v168, v162, v246
	ds_bpermute_b32 v169, v162, v247
	ds_bpermute_b32 v170, v162, v248
	ds_bpermute_b32 v171, v162, v249
	s_branch .LBB0_86

; __device__ __forceinline__ unsigned cvtpk(float lo, float hi) { unsigned r; asm volatile("v_cvt_pk_bf16_f32 %0, %1, %2" : "=v"(r) : "v"(lo), "v"(hi)); return r; }
;     __device__ __forceinline__ void operator()(f32x4 (&acc)[2][2][4][2], const pg8::Unit& u, int wr, int wc, int fr, int fq) const {
;     ...
;             for (int m = 0; m < 4; ++m) {
;                 u16* op = hbuf + (size_t)(row0 + ai * 128 + m * 16) * DM + (u.pn & 3) * 256 + cin;
; #pragma unroll
;                 for (int bj = 0; bj < 2; ++bj) {
;                     f32x4 vv[2];
; #pragma unroll
;                     for (int n = 0; n < 2; ++n) {
;                         const unsigned a4 = ga[m][bj][n], b4 = gb[m][bj][n]; f32x4 v = acc[ai][bj][m][n];
; #pragma unroll
;                         for (int j = 0; j < 4; ++j) { const float ga_ = fmaxf((float)((a4 >> (8 * j)) & 255u), 1.f), gb_ = fmaxf((float)((b4 >> (8 * j)) & 255u), 1.f);
;                             v[j] *= last ? ga_ * (1.f / 255.f) : ga_ * __builtin_amdgcn_rcpf(gb_); }
;                         vv[n] = v; if (!last) acc[ai][bj][m][n] = v;
;                     }
;                     if (last) { u32x4 o = {cvtpk(vv[0][0], vv[0][1]), cvtpk(vv[0][2], vv[0][3]), cvtpk(vv[1][0], vv[1][1]), cvtpk(vv[1][2], vv[1][3])}; *(u32x4*)(op + bj * 128) = o; }
.LBB0_86:
	v_cvt_f32_ubyte0_e32 v185, v180
	v_rcp_f32_e32 v185, v185
	v_cvt_f32_ubyte0_e32 v187, v178
	v_cvt_f32_ubyte1_e32 v190, v178
	v_cndmask_b32_e64 v185, v185, v203, s[38:39]
	v_mul_f32_e32 v185, v187, v185
	v_cvt_f32_ubyte1_e32 v187, v180
	v_rcp_f32_e32 v187, v187
	v_cvt_f32_ubyte2_e32 v191, v178
	v_cndmask_b32_e64 v187, v187, v203, s[38:39]
	v_mul_f32_e32 v187, v190, v187
	v_cvt_f32_ubyte2_e32 v190, v180
	v_rcp_f32_e32 v190, v190
	v_cvt_f32_ubyte3_e32 v180, v180
	v_cvt_f32_ubyte3_e32 v178, v178
	v_cndmask_b32_e64 v190, v190, v203, s[38:39]
	v_mul_f32_e32 v190, v191, v190
	v_rcp_f32_e32 v191, v180
	v_mul_f32_e32 v180, v56, v190
	v_cvt_f32_ubyte1_e32 v243, v179
	v_cndmask_b32_e64 v190, v191, v203, s[38:39]
	v_mul_f32_e32 v178, v178, v190
	v_cvt_f32_ubyte0_e32 v190, v181
	v_rcp_f32_e32 v190, v190
	v_cvt_f32_ubyte0_e32 v191, v179
	v_cndmask_b32_e64 v190, v190, v203, s[38:39]
	v_mul_f32_e32 v190, v191, v190
	v_cvt_f32_ubyte1_e32 v191, v181
	v_rcp_f32_e32 v191, v191
	v_cvt_f32_ubyte2_e32 v244, v179
	v_lshlrev_b64 v[182:183], 11, v[182:183]
	v_cndmask_b32_e64 v191, v191, v203, s[38:39]
	v_mul_f32_e32 v191, v243, v191
	v_cvt_f32_ubyte2_e32 v243, v181
	v_rcp_f32_e32 v243, v243
	v_cvt_f32_ubyte3_e32 v181, v181
	v_cvt_f32_ubyte3_e32 v179, v179
	v_cndmask_b32_e64 v243, v243, v203, s[38:39]
	v_mul_f32_e32 v243, v244, v243
	v_rcp_f32_e32 v244, v181
	v_lshl_add_u64 v[182:183], s[12:13], 0, v[182:183]
	v_mul_f32_e32 v181, v52, v243
	v_cndmask_b32_e64 v243, v244, v203, s[38:39]
	v_lshl_add_u64 v[182:183], v[182:183], 0, s[30:31]
	v_mul_f32_e32 v179, v179, v243
	v_lshl_add_u64 v[182:183], v[182:183], 0, v[0:1]
	v_mul_f32_e32 v185, v54, v185
	v_mul_f32_e32 v187, v55, v187
	v_mul_f32_e32 v178, v57, v178
	v_mul_f32_e32 v190, v50, v190
	v_mul_f32_e32 v191, v51, v191
	s_and_b64 vcc, exec, s[40:41]
	v_mul_f32_e32 v179, v53, v179
	s_cbranch_vccnz .LBB0_88
	v_cvt_pk_bf16_f32 v244, v185, v187
	v_cvt_pk_bf16_f32 v245, v180, v178
	v_cvt_pk_bf16_f32 v246, v190, v191
	v_cvt_pk_bf16_f32 v247, v181, v179
	s_waitcnt lgkmcnt(0)
	global_store_dwordx4 v[166:167], v[168:171], off offset:256
	v_lshl_add_u64 v[166:167], v[182:183], 0, v[164:165]
	ds_bpermute_b32 v168, v162, v244
	ds_bpermute_b32 v169, v162, v245
	ds_bpermute_b32 v170, v162, v246
	ds_bpermute_b32 v171, v162, v247
	s_branch .LBB0_89

; __device__ __forceinline__ unsigned cvtpk(float lo, float hi) { unsigned r; asm volatile("v_cvt_pk_bf16_f32 %0, %1, %2" : "=v"(r) : "v"(lo), "v"(hi)); return r; }
;     __device__ __forceinline__ void operator()(f32x4 (&acc)[2][2][4][2], const pg8::Unit& u, int wr, int wc, int fr, int fq) const {
;     ...
;             for (int m = 0; m < 4; ++m) {
;                 u16* op = hbuf + (size_t)(row0 + ai * 128 + m * 16) * DM + (u.pn & 3) * 256 + cin;
; #pragma unroll
;                 for (int bj = 0; bj < 2; ++bj) {
;                     f32x4 vv[2];
; #pragma unroll
;                     for (int n = 0; n < 2; ++n) {
;                         const unsigned a4 = ga[m][bj][n], b4 = gb[m][bj][n]; f32x4 v = acc[ai][bj][m][n];
; #pragma unroll
;                         for (int j = 0; j < 4; ++j) { const float ga_ = fmaxf((float)((a4 >> (8 * j)) & 255u), 1.f), gb_ = fmaxf((float)((b4 >> (8 * j)) & 255u), 1.f);
;                             v[j] *= last ? ga_ * (1.f / 255.f) : ga_ * __builtin_amdgcn_rcpf(gb_); }
;                         vv[n] = v; if (!last) acc[ai][bj][m][n] = v;
;                     }
;                     if (last) { u32x4 o = {cvtpk(vv[0][0], vv[0][1]), cvtpk(vv[0][2], vv[0][3]), cvtpk(vv[1][0], vv[1][1]), cvtpk(vv[1][2], vv[1][3])}; *(u32x4*)(op + bj * 128) = o; }
.LBB0_89:
	v_cvt_f32_ubyte0_e32 v179, v174
	v_rcp_f32_e32 v179, v179
	v_cvt_f32_ubyte0_e32 v181, v176
	v_cvt_f32_ubyte1_e32 v190, v174
	v_cndmask_b32_e64 v179, v179, v203, s[38:39]
	v_mul_f32_e32 v179, v181, v179
	v_max_f32_e32 v181, 1.0, v190
	v_rcp_f32_e32 v181, v181
	v_cvt_f32_ubyte1_e32 v190, v176
	v_cvt_f32_ubyte2_e32 v191, v176
	v_cndmask_b32_e64 v181, v181, v203, s[38:39]
	v_mul_f32_e32 v181, v190, v181
	v_cvt_f32_ubyte2_e32 v190, v174
	v_rcp_f32_e32 v190, v190
	v_cvt_f32_ubyte3_e32 v174, v174
	v_cndmask_b32_e64 v190, v190, v203, s[38:39]
	v_mul_f32_e32 v190, v191, v190
	v_rcp_f32_e32 v191, v174
	v_cvt_f32_ubyte3_e32 v176, v176
	v_mul_f32_e32 v174, v24, v190
	v_cndmask_b32_e64 v190, v191, v203, s[38:39]
	v_mul_f32_e32 v176, v176, v190
	v_cvt_f32_ubyte0_e32 v190, v175
	v_rcp_f32_e32 v190, v190
	v_cvt_f32_ubyte0_e32 v191, v177
	v_cvt_f32_ubyte1_e32 v243, v177
	v_cndmask_b32_e64 v190, v190, v203, s[38:39]
	v_mul_f32_e32 v190, v191, v190
	v_cvt_f32_ubyte1_e32 v191, v175
	v_rcp_f32_e32 v191, v191
	v_cvt_f32_ubyte2_e32 v244, v177
	v_cndmask_b32_e64 v191, v191, v203, s[38:39]
	v_mul_f32_e32 v191, v243, v191
	v_cvt_f32_ubyte2_e32 v243, v175
	v_rcp_f32_e32 v243, v243
	v_cvt_f32_ubyte3_e32 v175, v175
	v_cvt_f32_ubyte3_e32 v177, v177
	v_cndmask_b32_e64 v243, v243, v203, s[38:39]
	v_mul_f32_e32 v243, v244, v243
	v_rcp_f32_e32 v244, v175
	v_mul_f32_e32 v175, v20, v243
	v_mul_f32_e32 v179, v22, v179
	v_cndmask_b32_e64 v243, v244, v203, s[38:39]
	v_mul_f32_e32 v177, v177, v243
	v_mul_f32_e32 v181, v23, v181
	v_mul_f32_e32 v176, v25, v176
	v_mul_f32_e32 v190, v18, v190
	v_mul_f32_e32 v191, v19, v191
	s_and_b64 vcc, exec, s[40:41]
	v_mul_f32_e32 v177, v21, v177
	s_cbranch_vccnz .LBB0_91
	v_cvt_pk_bf16_f32 v244, v179, v181
	v_cvt_pk_bf16_f32 v245, v174, v176
	v_cvt_pk_bf16_f32 v246, v190, v191
	v_cvt_pk_bf16_f32 v247, v175, v177
	s_waitcnt lgkmcnt(0)
	global_store_dwordx4 v[166:167], v[168:171], off
	v_lshl_add_u64 v[166:167], v[182:183], 0, v[164:165]
	ds_bpermute_b32 v168, v162, v244
	ds_bpermute_b32 v169, v162, v245
	ds_bpermute_b32 v170, v162, v246
	ds_bpermute_b32 v171, v162, v247
	s_branch .LBB0_92

; __device__ __forceinline__ unsigned cvtpk(float lo, float hi) { unsigned r; asm volatile("v_cvt_pk_bf16_f32 %0, %1, %2" : "=v"(r) : "v"(lo), "v"(hi)); return r; }
;     __device__ __forceinline__ void operator()(f32x4 (&acc)[2][2][4][2], const pg8::Unit& u, int wr, int wc, int fr, int fq) const {
;     ...
;                         const unsigned a4 = ga[m][bj][n], b4 = gb[m][bj][n]; f32x4 v = acc[ai][bj][m][n];
; #pragma unroll
;                         for (int j = 0; j < 4; ++j) { const float ga_ = fmaxf((float)((a4 >> (8 * j)) & 255u), 1.f), gb_ = fmaxf((float)((b4 >> (8 * j)) & 255u), 1.f);
;                             v[j] *= last ? ga_ * (1.f / 255.f) : ga_ * __builtin_amdgcn_rcpf(gb_); }
;                         vv[n] = v; if (!last) acc[ai][bj][m][n] = v;
;                     }
;                     if (last) { u32x4 o = {cvtpk(vv[0][0], vv[0][1]), cvtpk(vv[0][2], vv[0][3]), cvtpk(vv[1][0], vv[1][1]), cvtpk(vv[1][2], vv[1][3])}; *(u32x4*)(op + bj * 128) = o; }
.LBB0_92:
	v_cvt_f32_ubyte0_e32 v175, v160
	v_rcp_f32_e32 v175, v175
	v_cvt_f32_ubyte0_e32 v177, v158
	v_cvt_f32_ubyte1_e32 v182, v158
	v_cndmask_b32_e64 v175, v175, v203, s[38:39]
	v_mul_f32_e32 v175, v177, v175
	v_cvt_f32_ubyte1_e32 v177, v160
	v_rcp_f32_e32 v177, v177
	v_cvt_f32_ubyte2_e32 v183, v158
	v_cndmask_b32_e64 v177, v177, v203, s[38:39]
	v_mul_f32_e32 v177, v182, v177
	v_cvt_f32_ubyte2_e32 v182, v160
	v_rcp_f32_e32 v182, v182
	v_cvt_f32_ubyte3_e32 v160, v160
	v_cvt_f32_ubyte3_e32 v158, v158
	v_cndmask_b32_e64 v182, v182, v203, s[38:39]
	v_mul_f32_e32 v182, v183, v182
	v_rcp_f32_e32 v183, v160
	v_mul_f32_e32 v160, v48, v182
	v_cvt_f32_ubyte1_e32 v190, v159
	v_cndmask_b32_e64 v182, v183, v203, s[38:39]
	v_mul_f32_e32 v158, v158, v182
	v_cvt_f32_ubyte0_e32 v182, v161
	v_rcp_f32_e32 v182, v182
	v_cvt_f32_ubyte0_e32 v183, v159
	v_cndmask_b32_e64 v182, v182, v203, s[38:39]
	v_mul_f32_e32 v182, v183, v182
	v_cvt_f32_ubyte1_e32 v183, v161
	v_rcp_f32_e32 v183, v183
	v_cvt_f32_ubyte2_e32 v191, v159
	v_lshlrev_b64 v[172:173], 11, v[172:173]
	v_cndmask_b32_e64 v183, v183, v203, s[38:39]
	v_mul_f32_e32 v183, v190, v183
	v_cvt_f32_ubyte2_e32 v190, v161
	v_rcp_f32_e32 v190, v190
	v_cvt_f32_ubyte3_e32 v161, v161
	v_cvt_f32_ubyte3_e32 v159, v159
	v_cndmask_b32_e64 v190, v190, v203, s[38:39]
	v_mul_f32_e32 v190, v191, v190
	v_rcp_f32_e32 v191, v161
	v_lshl_add_u64 v[172:173], s[12:13], 0, v[172:173]
	v_mul_f32_e32 v161, v44, v190
	v_cndmask_b32_e64 v190, v191, v203, s[38:39]
	v_lshl_add_u64 v[172:173], v[172:173], 0, s[30:31]
	v_mul_f32_e32 v159, v159, v190
	v_lshl_add_u64 v[172:173], v[172:173], 0, v[0:1]
	v_mul_f32_e32 v175, v46, v175
	v_mul_f32_e32 v177, v47, v177
	v_mul_f32_e32 v158, v49, v158
	v_mul_f32_e32 v182, v42, v182
	v_mul_f32_e32 v183, v43, v183
	s_and_b64 vcc, exec, s[40:41]
	v_mul_f32_e32 v159, v45, v159
	s_cbranch_vccnz .LBB0_94
	v_cvt_pk_bf16_f32 v244, v175, v177
	v_cvt_pk_bf16_f32 v245, v160, v158
	v_cvt_pk_bf16_f32 v246, v182, v183
	v_cvt_pk_bf16_f32 v247, v161, v159
	s_waitcnt lgkmcnt(0)
	global_store_dwordx4 v[166:167], v[168:171], off offset:256
	v_lshl_add_u64 v[166:167], v[172:173], 0, v[164:165]
	ds_bpermute_b32 v168, v162, v244
	ds_bpermute_b32 v169, v162, v245
	ds_bpermute_b32 v170, v162, v246
	ds_bpermute_b32 v171, v162, v247
	s_branch .LBB0_95

; __device__ __forceinline__ unsigned cvtpk(float lo, float hi) { unsigned r; asm volatile("v_cvt_pk_bf16_f32 %0, %1, %2" : "=v"(r) : "v"(lo), "v"(hi)); return r; }
;     __device__ __forceinline__ void operator()(f32x4 (&acc)[2][2][4][2], const pg8::Unit& u, int wr, int wc, int fr, int fq) const {
;     ...
;                         const unsigned a4 = ga[m][bj][n], b4 = gb[m][bj][n]; f32x4 v = acc[ai][bj][m][n];
; #pragma unroll
;                         for (int j = 0; j < 4; ++j) { const float ga_ = fmaxf((float)((a4 >> (8 * j)) & 255u), 1.f), gb_ = fmaxf((float)((b4 >> (8 * j)) & 255u), 1.f);
;                             v[j] *= last ? ga_ * (1.f / 255.f) : ga_ * __builtin_amdgcn_rcpf(gb_); }
;                         vv[n] = v; if (!last) acc[ai][bj][m][n] = v;
;                     }
;                     if (last) { u32x4 o = {cvtpk(vv[0][0], vv[0][1]), cvtpk(vv[0][2], vv[0][3]), cvtpk(vv[1][0], vv[1][1]), cvtpk(vv[1][2], vv[1][3])}; *(u32x4*)(op + bj * 128) = o; }
.LBB0_95:
	v_cvt_f32_ubyte0_e32 v159, v154
	v_rcp_f32_e32 v159, v159
	v_cvt_f32_ubyte0_e32 v161, v156
	v_cvt_f32_ubyte1_e32 v182, v154
	v_cndmask_b32_e64 v159, v159, v203, s[38:39]
	v_mul_f32_e32 v159, v161, v159
	v_max_f32_e32 v161, 1.0, v182
	v_rcp_f32_e32 v161, v161
	v_cvt_f32_ubyte1_e32 v182, v156
	v_cvt_f32_ubyte2_e32 v183, v156
	v_cndmask_b32_e64 v161, v161, v203, s[38:39]
	v_mul_f32_e32 v161, v182, v161
	v_cvt_f32_ubyte2_e32 v182, v154
	v_rcp_f32_e32 v182, v182
	v_cvt_f32_ubyte3_e32 v154, v154
	v_cndmask_b32_e64 v182, v182, v203, s[38:39]
	v_mul_f32_e32 v182, v183, v182
	v_rcp_f32_e32 v183, v154
	v_cvt_f32_ubyte3_e32 v156, v156
	v_mul_f32_e32 v154, v16, v182
	v_cndmask_b32_e64 v182, v183, v203, s[38:39]
	v_mul_f32_e32 v156, v156, v182
	v_cvt_f32_ubyte0_e32 v182, v155
	v_rcp_f32_e32 v182, v182
	v_cvt_f32_ubyte0_e32 v183, v157
	v_cvt_f32_ubyte1_e32 v190, v157
	v_cndmask_b32_e64 v182, v182, v203, s[38:39]
	v_mul_f32_e32 v182, v183, v182
	v_cvt_f32_ubyte1_e32 v183, v155
	v_rcp_f32_e32 v183, v183
	v_cvt_f32_ubyte2_e32 v191, v157
	v_cndmask_b32_e64 v183, v183, v203, s[38:39]
	v_mul_f32_e32 v183, v190, v183
	v_cvt_f32_ubyte2_e32 v190, v155
	v_rcp_f32_e32 v190, v190
	v_cvt_f32_ubyte3_e32 v155, v155
	v_cvt_f32_ubyte3_e32 v157, v157
	v_cndmask_b32_e64 v190, v190, v203, s[38:39]
	v_mul_f32_e32 v190, v191, v190
	v_rcp_f32_e32 v191, v155
	v_mul_f32_e32 v155, v12, v190
	v_mul_f32_e32 v159, v14, v159
	v_cndmask_b32_e64 v190, v191, v203, s[38:39]
	v_mul_f32_e32 v157, v157, v190
	v_mul_f32_e32 v161, v15, v161
	v_mul_f32_e32 v156, v17, v156
	v_mul_f32_e32 v182, v10, v182
	v_mul_f32_e32 v183, v11, v183
	s_and_b64 vcc, exec, s[40:41]
	v_mul_f32_e32 v157, v13, v157
	s_cbranch_vccnz .LBB0_97
	v_cvt_pk_bf16_f32 v244, v159, v161
	v_cvt_pk_bf16_f32 v245, v154, v156
	v_cvt_pk_bf16_f32 v246, v182, v183
	v_cvt_pk_bf16_f32 v247, v155, v157
	s_waitcnt lgkmcnt(0)
	global_store_dwordx4 v[166:167], v[168:171], off
	v_lshl_add_u64 v[166:167], v[172:173], 0, v[164:165]
	ds_bpermute_b32 v168, v162, v244
	ds_bpermute_b32 v169, v162, v245
	ds_bpermute_b32 v170, v162, v246
	ds_bpermute_b32 v171, v162, v247
	s_branch .LBB0_98

; __device__ __forceinline__ unsigned cvtpk(float lo, float hi) { unsigned r; asm volatile("v_cvt_pk_bf16_f32 %0, %1, %2" : "=v"(r) : "v"(lo), "v"(hi)); return r; }
;     __device__ __forceinline__ void operator()(f32x4 (&acc)[2][2][4][2], const pg8::Unit& u, int wr, int wc, int fr, int fq) const {
;     ...
;                         const unsigned a4 = ga[m][bj][n], b4 = gb[m][bj][n]; f32x4 v = acc[ai][bj][m][n];
; #pragma unroll
;                         for (int j = 0; j < 4; ++j) { const float ga_ = fmaxf((float)((a4 >> (8 * j)) & 255u), 1.f), gb_ = fmaxf((float)((b4 >> (8 * j)) & 255u), 1.f);
;                             v[j] *= last ? ga_ * (1.f / 255.f) : ga_ * __builtin_amdgcn_rcpf(gb_); }
;                         vv[n] = v; if (!last) acc[ai][bj][m][n] = v;
;                     }
;                     if (last) { u32x4 o = {cvtpk(vv[0][0], vv[0][1]), cvtpk(vv[0][2], vv[0][3]), cvtpk(vv[1][0], vv[1][1]), cvtpk(vv[1][2], vv[1][3])}; *(u32x4*)(op + bj * 128) = o; }
.LBB0_98:
	v_cvt_f32_ubyte0_e32 v155, v150
	v_rcp_f32_e32 v155, v155
	v_cvt_f32_ubyte0_e32 v157, v148
	v_cvt_f32_ubyte1_e32 v172, v148
	v_cndmask_b32_e64 v155, v155, v203, s[38:39]
	v_mul_f32_e32 v155, v157, v155
	v_cvt_f32_ubyte1_e32 v157, v150
	v_rcp_f32_e32 v157, v157
	v_cvt_f32_ubyte2_e32 v173, v148
	v_cndmask_b32_e64 v157, v157, v203, s[38:39]
	v_mul_f32_e32 v157, v172, v157
	v_cvt_f32_ubyte2_e32 v172, v150
	v_rcp_f32_e32 v172, v172
	v_cvt_f32_ubyte3_e32 v150, v150
	v_cvt_f32_ubyte3_e32 v148, v148
	v_cndmask_b32_e64 v172, v172, v203, s[38:39]
	v_mul_f32_e32 v172, v173, v172
	v_rcp_f32_e32 v173, v150
	v_mul_f32_e32 v150, v40, v172
	v_cvt_f32_ubyte1_e32 v182, v149
	v_cndmask_b32_e64 v172, v173, v203, s[38:39]
	v_mul_f32_e32 v148, v148, v172
	v_cvt_f32_ubyte0_e32 v172, v151
	v_rcp_f32_e32 v172, v172
	v_cvt_f32_ubyte0_e32 v173, v149
	v_cndmask_b32_e64 v172, v172, v203, s[38:39]
	v_mul_f32_e32 v172, v173, v172
	v_cvt_f32_ubyte1_e32 v173, v151
	v_rcp_f32_e32 v173, v173
	v_cvt_f32_ubyte2_e32 v183, v149
	v_lshlrev_b64 v[152:153], 11, v[152:153]
	v_cndmask_b32_e64 v173, v173, v203, s[38:39]
	v_mul_f32_e32 v173, v182, v173
	v_cvt_f32_ubyte2_e32 v182, v151
	v_rcp_f32_e32 v182, v182
	v_cvt_f32_ubyte3_e32 v151, v151
	v_cvt_f32_ubyte3_e32 v149, v149
	v_cndmask_b32_e64 v182, v182, v203, s[38:39]
	v_mul_f32_e32 v182, v183, v182
	v_rcp_f32_e32 v183, v151
	v_lshl_add_u64 v[152:153], s[12:13], 0, v[152:153]
	v_mul_f32_e32 v151, v36, v182
	v_cndmask_b32_e64 v182, v183, v203, s[38:39]
	v_lshl_add_u64 v[152:153], v[152:153], 0, s[30:31]
	v_mul_f32_e32 v149, v149, v182
	v_lshl_add_u64 v[152:153], v[152:153], 0, v[0:1]
	v_mul_f32_e32 v155, v38, v155
	v_mul_f32_e32 v157, v39, v157
	v_mul_f32_e32 v148, v41, v148
	v_mul_f32_e32 v172, v34, v172
	v_mul_f32_e32 v173, v35, v173
	s_and_b64 vcc, exec, s[40:41]
	v_mul_f32_e32 v149, v37, v149
	s_cbranch_vccnz .LBB0_100
	v_cvt_pk_bf16_f32 v244, v155, v157
	v_cvt_pk_bf16_f32 v245, v150, v148
	v_cvt_pk_bf16_f32 v246, v172, v173
	v_cvt_pk_bf16_f32 v247, v151, v149
	s_waitcnt lgkmcnt(0)
	global_store_dwordx4 v[166:167], v[168:171], off offset:256
	v_lshl_add_u64 v[166:167], v[152:153], 0, v[164:165]
	ds_bpermute_b32 v168, v162, v244
	ds_bpermute_b32 v169, v162, v245
	ds_bpermute_b32 v170, v162, v246
	ds_bpermute_b32 v171, v162, v247
	s_branch .LBB0_101

; __device__ __forceinline__ unsigned cvtpk(float lo, float hi) { unsigned r; asm volatile("v_cvt_pk_bf16_f32 %0, %1, %2" : "=v"(r) : "v"(lo), "v"(hi)); return r; }
;     __device__ __forceinline__ void operator()(f32x4 (&acc)[2][2][4][2], const pg8::Unit& u, int wr, int wc, int fr, int fq) const {
;     ...
;                         const unsigned a4 = ga[m][bj][n], b4 = gb[m][bj][n]; f32x4 v = acc[ai][bj][m][n];
; #pragma unroll
;                         for (int j = 0; j < 4; ++j) { const float ga_ = fmaxf((float)((a4 >> (8 * j)) & 255u), 1.f), gb_ = fmaxf((float)((b4 >> (8 * j)) & 255u), 1.f);
;                             v[j] *= last ? ga_ * (1.f / 255.f) : ga_ * __builtin_amdgcn_rcpf(gb_); }
;                         vv[n] = v; if (!last) acc[ai][bj][m][n] = v;
;                     }
;                     if (last) { u32x4 o = {cvtpk(vv[0][0], vv[0][1]), cvtpk(vv[0][2], vv[0][3]), cvtpk(vv[1][0], vv[1][1]), cvtpk(vv[1][2], vv[1][3])}; *(u32x4*)(op + bj * 128) = o; }
.LBB0_101:
	v_cvt_f32_ubyte0_e32 v149, v144
	v_rcp_f32_e32 v149, v149
	v_cvt_f32_ubyte0_e32 v151, v146
	v_cvt_f32_ubyte1_e32 v172, v144
	v_cndmask_b32_e64 v149, v149, v203, s[38:39]
	v_mul_f32_e32 v149, v151, v149
	v_max_f32_e32 v151, 1.0, v172
	v_rcp_f32_e32 v151, v151
	v_cvt_f32_ubyte1_e32 v172, v146
	v_cvt_f32_ubyte2_e32 v173, v146
	v_cndmask_b32_e64 v151, v151, v203, s[38:39]
	v_mul_f32_e32 v151, v172, v151
	v_cvt_f32_ubyte2_e32 v172, v144
	v_rcp_f32_e32 v172, v172
	v_cvt_f32_ubyte3_e32 v144, v144
	v_cndmask_b32_e64 v172, v172, v203, s[38:39]
	v_mul_f32_e32 v172, v173, v172
	v_rcp_f32_e32 v173, v144
	v_cvt_f32_ubyte3_e32 v146, v146
	v_mul_f32_e32 v144, v8, v172
	v_cndmask_b32_e64 v172, v173, v203, s[38:39]
	v_mul_f32_e32 v146, v146, v172
	v_cvt_f32_ubyte0_e32 v172, v145
	v_rcp_f32_e32 v172, v172
	v_cvt_f32_ubyte0_e32 v173, v147
	v_cvt_f32_ubyte1_e32 v182, v147
	v_cndmask_b32_e64 v172, v172, v203, s[38:39]
	v_mul_f32_e32 v172, v173, v172
	v_cvt_f32_ubyte1_e32 v173, v145
	v_rcp_f32_e32 v173, v173
	v_cvt_f32_ubyte2_e32 v183, v147
	v_cndmask_b32_e64 v173, v173, v203, s[38:39]
	v_mul_f32_e32 v173, v182, v173
	v_cvt_f32_ubyte2_e32 v182, v145
	v_rcp_f32_e32 v182, v182
	v_cvt_f32_ubyte3_e32 v145, v145
	v_cvt_f32_ubyte3_e32 v147, v147
	v_cndmask_b32_e64 v182, v182, v203, s[38:39]
	v_mul_f32_e32 v182, v183, v182
	v_rcp_f32_e32 v183, v145
	v_mul_f32_e32 v145, v4, v182
	v_mul_f32_e32 v149, v6, v149
	v_cndmask_b32_e64 v182, v183, v203, s[38:39]
	v_mul_f32_e32 v147, v147, v182
	v_mul_f32_e32 v151, v7, v151
	v_mul_f32_e32 v146, v9, v146
	v_mul_f32_e32 v172, v2, v172
	v_mul_f32_e32 v173, v3, v173
	s_and_b64 vcc, exec, s[40:41]
	v_mul_f32_e32 v147, v5, v147
	s_cbranch_vccnz .LBB0_103
	v_cvt_pk_bf16_f32 v244, v149, v151
	v_cvt_pk_bf16_f32 v245, v144, v146
	v_cvt_pk_bf16_f32 v246, v172, v173
	v_cvt_pk_bf16_f32 v247, v145, v147
	s_waitcnt lgkmcnt(0)
	global_store_dwordx4 v[166:167], v[168:171], off
	v_lshl_add_u64 v[166:167], v[152:153], 0, v[164:165]
	ds_bpermute_b32 v168, v162, v244
	ds_bpermute_b32 v169, v162, v245
	ds_bpermute_b32 v170, v162, v246
	ds_bpermute_b32 v171, v162, v247
	s_waitcnt lgkmcnt(0)
	global_store_dwordx4 v[166:167], v[168:171], off offset:256
	v_mov_b32_e32 v162, 0x3f317218
	v_mov_b64_e32 v[164:165], 0xaff
	s_nop 1
	v_mov_b64_e32 v[166:167], 0xb00
	v_mov_b64_e32 v[168:169], 0xff
	v_mov_b64_e32 v[170:171], 0x100
	s_mov_b64 s[20:21], -1
	s_and_b64 vcc, exec, s[34:35]
	s_cbranch_vccz .LBB0_21
	s_branch .LBB0_104
